# attention: the -m accumulator-init block kept in 16 otherwise unused registers and rebuilt only when the running max changes (17 fewer VALU per 64-key half-step)
# speedup vs baseline: 1.0011x; 1.0011x over previous
.LBB0_540:
	v_add_u32_e32 v3, s33, v195
	s_movk_i32 s0, 0x7ff
	v_cmp_lt_i32_e32 vcc, s0, v3
	s_and_saveexec_b64 s[0:1], vcc
	s_xor_b64 s[0:1], exec, s[0:1]
	v_add_u32_e32 v2, 0xfffff800, v3
	v_lshrrev_b32_e32 v6, 5, v2
	v_lshrrev_b32_e32 v4, 1, v3
	v_lshrrev_b32_e32 v0, 4, v3
	v_lshl_add_u32 v2, v6, 8, v135
	s_or_saveexec_b64 s[0:1], s[0:1]
	v_mov_b32_e32 v204, 4
	v_mov_b32_e32 v5, v129
	s_xor_b64 exec, exec, s[0:1]
	v_lshlrev_b32_e32 v2, 7, v3
	v_ashrrev_i32_e32 v6, 8, v3
	v_and_b32_e32 v2, 0x780, v2
	v_lshrrev_b32_e32 v4, 4, v3
	v_lshrrev_b32_e32 v0, 7, v3
	v_add_u32_e32 v5, 0x100, v2
	v_lshl_or_b32 v2, v6, 11, v2
	v_mov_b32_e32 v204, 36
	s_or_b64 exec, exec, s[0:1]
	v_ashrrev_i32_e32 v3, 31, v2
	v_and_b32_e32 v7, 1, v0
	v_lshlrev_b64 v[2:3], 11, v[2:3]
	v_and_b32_e32 v22, 7, v4
	v_lshl_add_u64 v[2:3], s[88:89], 0, v[2:3]
	v_lshlrev_b32_e32 v0, 10, v7
	v_lshl_add_u64 v[2:3], v[2:3], 0, v[0:1]
	v_lshlrev_b32_e32 v0, 7, v22
	v_lshl_add_u64 v[180:181], v[2:3], 0, v[0:1]
	v_cmp_eq_u32_e32 vcc, 1, v7
	s_and_saveexec_b64 s[0:1], vcc
	s_xor_b64 s[0:1], exec, s[0:1]
	s_cbranch_execz .LBB0_558
	v_mul_lo_u32 v2, v6, s20
	v_add_u32_e32 v8, v2, v5
	v_ashrrev_i32_e32 v9, 31, v8
	v_lshlrev_b32_e32 v0, 6, v22
	v_lshlrev_b64 v[8:9], 10, v[8:9]
	v_ashrrev_i32_e32 v3, 31, v2
	v_lshrrev_b32_e32 v7, 2, v22
	v_lshl_add_u64 v[8:9], s[8:9], 0, v[8:9]
	v_lshlrev_b32_e32 v0, 1, v0
	v_lshlrev_b64 v[16:17], 8, v[2:3]
	v_lshl_add_u64 v[8:9], v[8:9], 0, v[0:1]
	v_lshl_add_u64 v[2:3], s[10:11], 0, v[16:17]
	v_lshlrev_b32_e32 v0, 7, v7
	v_mov_b32_e32 v171, v1
	v_lshl_add_u64 v[2:3], v[2:3], 0, v[0:1]
	v_lshl_or_b32 v0, v6, 1, v7
	v_lshl_add_u64 v[6:7], v[8:9], 0, v[170:171]
	v_mov_b32_e32 v177, v1
	v_lshl_add_u64 v[6:7], v[6:7], 0, v[176:177]
	v_mov_b32_e32 v173, v1
	global_load_dwordx4 v[80:83], v[6:7], off
	global_load_dwordx4 v[84:87], v[6:7], off offset:32
	global_load_dwordx4 v[88:91], v[6:7], off offset:64
	global_load_dwordx4 v[92:95], v[6:7], off offset:96
	v_lshl_add_u64 v[2:3], v[2:3], 0, v[172:173]
	v_mov_b32_e32 v179, v1
	v_mad_i64_i32 v[6:7], s[6:7], v0, s25, v[156:157]
	v_lshl_add_u64 v[2:3], v[2:3], 0, v[178:179]
	s_movk_i32 s6, 0x4000
	v_add_co_u32_e32 v8, vcc, s6, v2
	s_mov_b32 s6, 0x8000
	s_nop 0
	v_addc_co_u32_e32 v9, vcc, 0, v3, vcc
	global_load_dwordx4 v[48:51], v[2:3], off
	global_load_dwordx4 v[52:55], v[6:7], off
	v_add_co_u32_e32 v2, vcc, s6, v2
	v_and_b32_e32 v19, 4, v4
	s_nop 0
	v_addc_co_u32_e32 v3, vcc, 0, v3, vcc
	global_load_dwordx4 v[96:99], v[8:9], off
	global_load_dwordx4 v[104:107], v[6:7], off offset:128
	global_load_dwordx4 v[100:103], v[2:3], off
	global_load_dwordx4 v[108:111], v[6:7], off offset:256
	v_cmp_lt_i32_e32 vcc, v200, v201
	v_mov_b32_e32 v14, v1
	v_mov_b32_e32 v15, v1
	v_cndmask_b32_e32 v18, v199, v200, vcc
	v_lshl_or_b32 v16, v19, 5, v16
	v_mov_b32_e32 v2, v1
	v_mov_b32_e32 v3, v1
	v_mov_b32_e32 v4, v1
	v_mov_b32_e32 v5, v1
	v_mov_b32_e32 v6, v1
	v_mov_b32_e32 v7, v1
	v_mov_b32_e32 v8, v1
	v_mov_b32_e32 v9, v1
	v_mov_b32_e32 v10, v1
	v_mov_b32_e32 v11, v1
	v_mov_b32_e32 v12, v1
	v_mov_b32_e32 v13, v1
	s_waitcnt vmcnt(15)
	v_lshlrev_b32_e32 v116, 2, v18
	v_mad_i64_i32 v[112:113], s[16:17], v0, s25, v[154:155]
	v_lshl_add_u64 v[114:115], v[162:163], 0, v[16:17]
	v_mov_b32_e32 v0, v1
	v_mov_b64_e32 v[30:31], v[14:15]
	v_mov_b64_e32 v[46:47], v[14:15]
	s_mov_b32 s28, 4
	v_mov_b32_e32 v117, 0
	s_mov_b64 s[6:7], 0
	v_mov_b64_e32 v[28:29], v[12:13]
	v_mov_b64_e32 v[26:27], v[10:11]
	v_mov_b64_e32 v[24:25], v[8:9]
	v_mov_b64_e32 v[22:23], v[6:7]
	v_mov_b64_e32 v[20:21], v[4:5]
	v_mov_b64_e32 v[18:19], v[2:3]
	v_mov_b64_e32 v[16:17], v[0:1]
	v_mov_b64_e32 v[44:45], v[12:13]
	v_mov_b64_e32 v[42:43], v[10:11]
	v_mov_b64_e32 v[40:41], v[8:9]
	v_mov_b64_e32 v[38:39], v[6:7]
	v_mov_b64_e32 v[36:37], v[4:5]
	v_mov_b64_e32 v[34:35], v[2:3]
	v_mov_b64_e32 v[32:33], v[0:1]
	v_mov_b32_e32 v0, 0
	v_xor_b32_e32 v234, 0x80000000, v0
	v_mov_b32_e32 v235, v234
	v_mov_b32_e32 v236, v234
	v_mov_b32_e32 v237, v234
	v_mov_b32_e32 v238, v234
	v_mov_b32_e32 v239, v234
	v_mov_b32_e32 v240, v234
	v_mov_b32_e32 v241, v234
	v_mov_b32_e32 v242, v234
	v_mov_b32_e32 v243, v234
	v_mov_b32_e32 v244, v234
	v_mov_b32_e32 v245, v234
	v_mov_b32_e32 v246, v234
	v_mov_b32_e32 v247, v234
	v_mov_b32_e32 v248, v234
	v_mov_b32_e32 v249, v234
	s_waitcnt vmcnt(5)
	ds_write_b128 v139, v[48:51]
	s_waitcnt vmcnt(4)
	ds_write_b64 v253, v[52:53] offset:9216
	ds_write_b64 v253, v[54:55] offset:9232
	s_waitcnt lgkmcnt(0)
	s_barrier
	s_branch .LBB0_547

.LBB0_547:
	ds_read_b128 v[2:5], v137
	ds_read_b128 v[6:9], v137 offset:32
	s_waitcnt lgkmcnt(1)
	s_nop 0
	v_mfma_f32_32x32x16_bf16 v[64:79], v[2:5], v[80:83], v[234:249]
	ds_read_b128 v[2:5], v137 offset:4608
	ds_read_b128 v[10:13], v137 offset:4640
	s_waitcnt lgkmcnt(1)
	v_mfma_f32_32x32x16_bf16 v[48:63], v[2:5], v[80:83], v[234:249]
	v_mfma_f32_32x32x16_bf16 v[64:79], v[6:9], v[84:87], v[64:79]
	ds_read_b128 v[2:5], v137 offset:64
	ds_read_b128 v[6:9], v137 offset:96
	s_waitcnt lgkmcnt(2)
	v_mfma_f32_32x32x16_bf16 v[48:63], v[10:13], v[84:87], v[48:63]
	s_waitcnt lgkmcnt(1)
	v_mfma_f32_32x32x16_bf16 v[64:79], v[2:5], v[88:91], v[64:79]
	ds_read_b128 v[2:5], v137 offset:4672
	ds_read_b128 v[10:13], v137 offset:4704
	s_waitcnt lgkmcnt(1)
	v_mfma_f32_32x32x16_bf16 v[48:63], v[2:5], v[88:91], v[48:63]
	s_waitcnt lgkmcnt(0)
	v_mfma_f32_32x32x16_bf16 v[48:63], v[10:13], v[92:95], v[48:63]
	v_mfma_f32_32x32x16_bf16 v[64:79], v[6:9], v[92:95], v[64:79]
	s_nop 10
	v_max_f32_e32 v2, v48, v48
	v_max_f32_e32 v3, v64, v64
	v_max_f32_e32 v2, v3, v2
	v_max3_f32 v2, v2, v65, v49
	v_max3_f32 v2, v2, v66, v50
	v_max3_f32 v2, v2, v67, v51
	v_max3_f32 v2, v2, v68, v52
	v_max3_f32 v2, v2, v69, v53
	v_max3_f32 v2, v2, v70, v54
	v_max3_f32 v2, v2, v71, v55
	v_max3_f32 v2, v2, v72, v56
	v_max3_f32 v2, v2, v73, v57
	v_max3_f32 v2, v2, v74, v58
	v_max3_f32 v2, v2, v75, v59
	v_max3_f32 v2, v2, v76, v60
	v_max3_f32 v2, v2, v77, v61
	v_max3_f32 v2, v2, v78, v62
	v_max3_f32 v2, v2, v79, v63
	ds_bpermute_b32 v3, v116, v2
	s_waitcnt lgkmcnt(0)
	v_max_f32_e32 v3, v3, v3
	v_max_f32_e32 v2, v2, v3
	v_cmp_lt_f32_e32 vcc, s26, v2
	s_cbranch_vccz .LBB0_549
	v_max_f32_e32 v2, v2, v2
	v_max_f32_e32 v2, 0, v2
	v_exp_f32_e64 v4, -v2
	v_pk_add_f32 v[64:65], v[64:65], v[2:3] op_sel_hi:[1,0] neg_lo:[0,1] neg_hi:[0,1]
	v_pk_add_f32 v[48:49], v[48:49], v[2:3] op_sel_hi:[1,0] neg_lo:[0,1] neg_hi:[0,1]
	v_pk_add_f32 v[66:67], v[66:67], v[2:3] op_sel_hi:[1,0] neg_lo:[0,1] neg_hi:[0,1]
	v_pk_add_f32 v[50:51], v[50:51], v[2:3] op_sel_hi:[1,0] neg_lo:[0,1] neg_hi:[0,1]
	v_pk_add_f32 v[68:69], v[68:69], v[2:3] op_sel_hi:[1,0] neg_lo:[0,1] neg_hi:[0,1]
	v_pk_add_f32 v[52:53], v[52:53], v[2:3] op_sel_hi:[1,0] neg_lo:[0,1] neg_hi:[0,1]
	v_pk_add_f32 v[70:71], v[70:71], v[2:3] op_sel_hi:[1,0] neg_lo:[0,1] neg_hi:[0,1]
	v_pk_add_f32 v[54:55], v[54:55], v[2:3] op_sel_hi:[1,0] neg_lo:[0,1] neg_hi:[0,1]
	v_pk_add_f32 v[72:73], v[72:73], v[2:3] op_sel_hi:[1,0] neg_lo:[0,1] neg_hi:[0,1]
	v_pk_add_f32 v[56:57], v[56:57], v[2:3] op_sel_hi:[1,0] neg_lo:[0,1] neg_hi:[0,1]
	v_pk_add_f32 v[74:75], v[74:75], v[2:3] op_sel_hi:[1,0] neg_lo:[0,1] neg_hi:[0,1]
	v_pk_add_f32 v[58:59], v[58:59], v[2:3] op_sel_hi:[1,0] neg_lo:[0,1] neg_hi:[0,1]
	v_pk_add_f32 v[76:77], v[76:77], v[2:3] op_sel_hi:[1,0] neg_lo:[0,1] neg_hi:[0,1]
	v_pk_add_f32 v[60:61], v[60:61], v[2:3] op_sel_hi:[1,0] neg_lo:[0,1] neg_hi:[0,1]
	v_pk_mul_f32 v[46:47], v[46:47], v[4:5] op_sel_hi:[1,0]
	v_pk_mul_f32 v[44:45], v[44:45], v[4:5] op_sel_hi:[1,0]
	v_pk_mul_f32 v[42:43], v[42:43], v[4:5] op_sel_hi:[1,0]
	v_pk_mul_f32 v[40:41], v[40:41], v[4:5] op_sel_hi:[1,0]
	v_pk_mul_f32 v[38:39], v[38:39], v[4:5] op_sel_hi:[1,0]
	v_pk_mul_f32 v[36:37], v[36:37], v[4:5] op_sel_hi:[1,0]
	v_pk_mul_f32 v[34:35], v[34:35], v[4:5] op_sel_hi:[1,0]
	v_pk_mul_f32 v[32:33], v[32:33], v[4:5] op_sel_hi:[1,0]
	v_pk_mul_f32 v[30:31], v[30:31], v[4:5] op_sel_hi:[1,0]
	v_pk_mul_f32 v[28:29], v[28:29], v[4:5] op_sel_hi:[1,0]
	v_pk_mul_f32 v[26:27], v[26:27], v[4:5] op_sel_hi:[1,0]
	v_pk_mul_f32 v[24:25], v[24:25], v[4:5] op_sel_hi:[1,0]
	v_pk_mul_f32 v[22:23], v[22:23], v[4:5] op_sel_hi:[1,0]
	v_pk_mul_f32 v[20:21], v[20:21], v[4:5] op_sel_hi:[1,0]
	v_pk_mul_f32 v[18:19], v[18:19], v[4:5] op_sel_hi:[1,0]
	v_pk_mul_f32 v[16:17], v[16:17], v[4:5] op_sel_hi:[1,0]
	v_pk_add_f32 v[78:79], v[78:79], v[2:3] op_sel_hi:[1,0] neg_lo:[0,1] neg_hi:[0,1]
	v_pk_add_f32 v[62:63], v[62:63], v[2:3] op_sel_hi:[1,0] neg_lo:[0,1] neg_hi:[0,1]
	v_mul_f32_e32 v117, v117, v4
	v_add_f32_e32 v0, v0, v2
	v_xor_b32_e32 v234, 0x80000000, v0
	v_mov_b32_e32 v235, v234
	v_mov_b32_e32 v236, v234
	v_mov_b32_e32 v237, v234
	v_mov_b32_e32 v238, v234
	v_mov_b32_e32 v239, v234
	v_mov_b32_e32 v240, v234
	v_mov_b32_e32 v241, v234
	v_mov_b32_e32 v242, v234
	v_mov_b32_e32 v243, v234
	v_mov_b32_e32 v244, v234
	v_mov_b32_e32 v245, v234
	v_mov_b32_e32 v246, v234
	v_mov_b32_e32 v247, v234
	v_mov_b32_e32 v248, v234
	v_mov_b32_e32 v249, v234

.LBB0_551:
	s_or_b64 exec, exec, s[16:17]
	s_waitcnt lgkmcnt(0)
	s_barrier
	ds_read_b128 v[206:209], v137 offset:18432
	ds_read_b128 v[210:213], v137 offset:18464
	v_add_f32_e32 v6, 0, v6
	v_add_f32_e32 v6, v6, v7
	s_waitcnt lgkmcnt(1)
	v_mfma_f32_32x32x16_bf16 v[64:79], v[206:209], v[80:83], v[234:249]
	ds_read_b128 v[206:209], v137 offset:23040
	ds_read_b128 v[214:217], v137 offset:23072
	v_add_f32_e32 v6, v8, v6
	v_add_f32_e32 v185, v9, v6
	ds_read_b128 v[6:9], v137 offset:18496
	v_add_f32_e32 v2, v2, v185
	v_add_f32_e32 v2, v3, v2
	v_add_f32_e32 v2, v4, v2
	s_waitcnt lgkmcnt(2)
	v_mfma_f32_32x32x16_bf16 v[48:63], v[206:209], v[80:83], v[234:249]
	v_add_f32_e32 v2, v5, v2
	v_add_f32_e32 v15, v15, v2
	ds_read_b128 v[2:5], v137 offset:23104
	ds_read_b128 v[206:209], v137 offset:18528
	v_mfma_f32_32x32x16_bf16 v[64:79], v[210:213], v[84:87], v[64:79]
	s_waitcnt lgkmcnt(3)
	v_mfma_f32_32x32x16_bf16 v[48:63], v[214:217], v[84:87], v[48:63]
	s_waitcnt lgkmcnt(2)
	v_mfma_f32_32x32x16_bf16 v[64:79], v[6:9], v[88:91], v[64:79]
	v_add_f32_e32 v6, v10, v15
	v_add_f32_e32 v6, v11, v6
	v_add_f32_e32 v6, v119, v6
	v_add_f32_e32 v6, v120, v6
	v_add_f32_e32 v6, v121, v6
	v_add_f32_e32 v10, v122, v6
	ds_read_b128 v[6:9], v137 offset:23136
	s_waitcnt lgkmcnt(2)
	v_mfma_f32_32x32x16_bf16 v[48:63], v[2:5], v[88:91], v[48:63]
	v_add_f32_e32 v2, v118, v10
	v_add_f32_e32 v2, v123, v2
	v_add_f32_e32 v2, v124, v2
	v_add_f32_e32 v2, v125, v2
	v_add_f32_e32 v2, v171, v2
	v_add_f32_e32 v2, v173, v2
	v_add_f32_e32 v2, v175, v2
	s_waitcnt lgkmcnt(1)
	v_mfma_f32_32x32x16_bf16 v[64:79], v[206:209], v[92:95], v[64:79]
	v_add_f32_e32 v2, v126, v2
	v_add_f32_e32 v2, v127, v2
	v_add_f32_e32 v2, v177, v2
	v_add_f32_e32 v2, v179, v2
	v_add_f32_e32 v2, v182, v2
	v_add_f32_e32 v2, v183, v2
	v_add_f32_e32 v2, v184, v2
	s_waitcnt lgkmcnt(0)
	v_mfma_f32_32x32x16_bf16 v[48:63], v[6:9], v[92:95], v[48:63]
	s_nop 2
	v_max_f32_e32 v4, v64, v64
	v_add_f32_e32 v2, v12, v2
	v_add_f32_e32 v2, v13, v2
	v_add_f32_e32 v2, v14, v2
	v_add_f32_e32 v2, v117, v2
	s_nop 3
	v_max_f32_e32 v3, v48, v48
	v_max_f32_e32 v3, v4, v3
	v_max3_f32 v3, v3, v65, v49
	v_max3_f32 v3, v3, v66, v50
	v_max3_f32 v3, v3, v67, v51
	v_max3_f32 v3, v3, v68, v52
	v_max3_f32 v3, v3, v69, v53
	v_max3_f32 v3, v3, v70, v54
	v_max3_f32 v3, v3, v71, v55
	v_max3_f32 v3, v3, v72, v56
	v_max3_f32 v3, v3, v73, v57
	v_max3_f32 v3, v3, v74, v58
	v_max3_f32 v3, v3, v75, v59
	v_max3_f32 v3, v3, v76, v60
	v_max3_f32 v3, v3, v77, v61
	v_max3_f32 v3, v3, v78, v62
	v_max3_f32 v3, v3, v79, v63
	ds_bpermute_b32 v4, v116, v3
	s_waitcnt lgkmcnt(0)
	v_max_f32_e32 v4, v4, v4
	v_max_f32_e32 v3, v3, v4
	v_cmp_lt_f32_e32 vcc, s26, v3
	s_cbranch_vccz .LBB0_553
	v_max_f32_e32 v3, v3, v3
	v_max_f32_e32 v4, 0, v3
	v_exp_f32_e64 v6, -v4
	v_pk_add_f32 v[64:65], v[64:65], v[4:5] op_sel_hi:[1,0] neg_lo:[0,1] neg_hi:[0,1]
	v_pk_add_f32 v[48:49], v[48:49], v[4:5] op_sel_hi:[1,0] neg_lo:[0,1] neg_hi:[0,1]
	v_pk_add_f32 v[66:67], v[66:67], v[4:5] op_sel_hi:[1,0] neg_lo:[0,1] neg_hi:[0,1]
	v_pk_add_f32 v[50:51], v[50:51], v[4:5] op_sel_hi:[1,0] neg_lo:[0,1] neg_hi:[0,1]
	v_pk_add_f32 v[68:69], v[68:69], v[4:5] op_sel_hi:[1,0] neg_lo:[0,1] neg_hi:[0,1]
	v_pk_add_f32 v[52:53], v[52:53], v[4:5] op_sel_hi:[1,0] neg_lo:[0,1] neg_hi:[0,1]
	v_pk_add_f32 v[70:71], v[70:71], v[4:5] op_sel_hi:[1,0] neg_lo:[0,1] neg_hi:[0,1]
	v_pk_add_f32 v[54:55], v[54:55], v[4:5] op_sel_hi:[1,0] neg_lo:[0,1] neg_hi:[0,1]
	v_pk_add_f32 v[72:73], v[72:73], v[4:5] op_sel_hi:[1,0] neg_lo:[0,1] neg_hi:[0,1]
	v_pk_add_f32 v[56:57], v[56:57], v[4:5] op_sel_hi:[1,0] neg_lo:[0,1] neg_hi:[0,1]
	v_pk_add_f32 v[74:75], v[74:75], v[4:5] op_sel_hi:[1,0] neg_lo:[0,1] neg_hi:[0,1]
	v_pk_add_f32 v[58:59], v[58:59], v[4:5] op_sel_hi:[1,0] neg_lo:[0,1] neg_hi:[0,1]
	v_pk_add_f32 v[76:77], v[76:77], v[4:5] op_sel_hi:[1,0] neg_lo:[0,1] neg_hi:[0,1]
	v_pk_add_f32 v[60:61], v[60:61], v[4:5] op_sel_hi:[1,0] neg_lo:[0,1] neg_hi:[0,1]
	v_pk_mul_f32 v[46:47], v[46:47], v[6:7] op_sel_hi:[1,0]
	v_pk_mul_f32 v[44:45], v[44:45], v[6:7] op_sel_hi:[1,0]
	v_pk_mul_f32 v[42:43], v[42:43], v[6:7] op_sel_hi:[1,0]
	v_pk_mul_f32 v[40:41], v[40:41], v[6:7] op_sel_hi:[1,0]
	v_pk_mul_f32 v[38:39], v[38:39], v[6:7] op_sel_hi:[1,0]
	v_pk_mul_f32 v[36:37], v[36:37], v[6:7] op_sel_hi:[1,0]
	v_pk_mul_f32 v[34:35], v[34:35], v[6:7] op_sel_hi:[1,0]
	v_pk_mul_f32 v[32:33], v[32:33], v[6:7] op_sel_hi:[1,0]
	v_pk_mul_f32 v[30:31], v[30:31], v[6:7] op_sel_hi:[1,0]
	v_pk_mul_f32 v[28:29], v[28:29], v[6:7] op_sel_hi:[1,0]
	v_pk_mul_f32 v[26:27], v[26:27], v[6:7] op_sel_hi:[1,0]
	v_pk_mul_f32 v[24:25], v[24:25], v[6:7] op_sel_hi:[1,0]
	v_pk_mul_f32 v[22:23], v[22:23], v[6:7] op_sel_hi:[1,0]
	v_pk_mul_f32 v[20:21], v[20:21], v[6:7] op_sel_hi:[1,0]
	v_pk_mul_f32 v[18:19], v[18:19], v[6:7] op_sel_hi:[1,0]
	v_pk_mul_f32 v[16:17], v[16:17], v[6:7] op_sel_hi:[1,0]
	v_pk_add_f32 v[78:79], v[78:79], v[4:5] op_sel_hi:[1,0] neg_lo:[0,1] neg_hi:[0,1]
	v_pk_add_f32 v[62:63], v[62:63], v[4:5] op_sel_hi:[1,0] neg_lo:[0,1] neg_hi:[0,1]
	v_mul_f32_e32 v2, v2, v6
	v_add_f32_e32 v0, v0, v4
	v_xor_b32_e32 v234, 0x80000000, v0
	v_mov_b32_e32 v235, v234
	v_mov_b32_e32 v236, v234
	v_mov_b32_e32 v237, v234
	v_mov_b32_e32 v238, v234
	v_mov_b32_e32 v239, v234
	v_mov_b32_e32 v240, v234
	v_mov_b32_e32 v241, v234
	v_mov_b32_e32 v242, v234
	v_mov_b32_e32 v243, v234
	v_mov_b32_e32 v244, v234
	v_mov_b32_e32 v245, v234
	v_mov_b32_e32 v246, v234
	v_mov_b32_e32 v247, v234
	v_mov_b32_e32 v248, v234
	v_mov_b32_e32 v249, v234

.LBB0_567:
	s_or_b64 exec, exec, s[0:1]
	global_load_dwordx4 v[124:127], v[18:19], off offset:256
	v_cmp_lt_i32_e32 vcc, v200, v201
	v_mad_i64_i32 v[2:3], s[0:1], v10, s24, v[164:165]
	s_nop 0
	v_cndmask_b32_e32 v0, v199, v200, vcc
	v_lshlrev_b32_e32 v171, 2, v0
	v_mad_u64_u32 v[182:183], s[0:1], v22, s27, v[2:3]
	v_add_u32_e32 v0, v11, v22
	v_mad_i64_i32 v[2:3], s[0:1], v10, s24, v[168:169]
	v_mov_b32_e32 v14, v1
	v_mov_b32_e32 v15, v1
	v_mad_i64_i32 v[184:185], s[0:1], v0, s25, v[166:167]
	v_mad_u64_u32 v[186:187], s[0:1], v22, s27, v[2:3]
	v_mov_b32_e32 v0, v1
	v_mov_b32_e32 v2, v1
	v_mov_b32_e32 v3, v1
	v_mov_b32_e32 v4, v1
	v_mov_b32_e32 v5, v1
	v_mov_b32_e32 v6, v1
	v_mov_b32_e32 v7, v1
	v_mov_b32_e32 v8, v1
	v_mov_b32_e32 v9, v1
	v_mov_b32_e32 v10, v1
	v_mov_b32_e32 v11, v1
	v_mov_b32_e32 v12, v1
	v_mov_b32_e32 v13, v1
	v_mov_b64_e32 v[30:31], v[14:15]
	v_mov_b64_e32 v[46:47], v[14:15]
	s_mov_b32 s28, 0
	v_mov_b32_e32 v173, 0
	s_mov_b64 s[0:1], 0
	v_mov_b64_e32 v[28:29], v[12:13]
	v_mov_b64_e32 v[26:27], v[10:11]
	v_mov_b64_e32 v[24:25], v[8:9]
	v_mov_b64_e32 v[22:23], v[6:7]
	v_mov_b64_e32 v[20:21], v[4:5]
	v_mov_b64_e32 v[18:19], v[2:3]
	v_mov_b64_e32 v[16:17], v[0:1]
	v_mov_b64_e32 v[44:45], v[12:13]
	v_mov_b64_e32 v[42:43], v[10:11]
	v_mov_b64_e32 v[40:41], v[8:9]
	v_mov_b64_e32 v[38:39], v[6:7]
	v_mov_b64_e32 v[36:37], v[4:5]
	v_mov_b64_e32 v[34:35], v[2:3]
	v_mov_b64_e32 v[32:33], v[0:1]
	v_mov_b32_e32 v0, 0
	v_xor_b32_e32 v234, 0x80000000, v0
	v_mov_b32_e32 v235, v234
	v_mov_b32_e32 v236, v234
	v_mov_b32_e32 v237, v234
	v_mov_b32_e32 v238, v234
	v_mov_b32_e32 v239, v234
	v_mov_b32_e32 v240, v234
	v_mov_b32_e32 v241, v234
	v_mov_b32_e32 v242, v234
	v_mov_b32_e32 v243, v234
	v_mov_b32_e32 v244, v234
	v_mov_b32_e32 v245, v234
	v_mov_b32_e32 v246, v234
	v_mov_b32_e32 v247, v234
	v_mov_b32_e32 v248, v234
	v_mov_b32_e32 v249, v234
	s_waitcnt lgkmcnt(0)
	s_barrier
	s_branch .LBB0_570

.LBB0_570:
	v_add_u32_e32 v14, v136, v151
	ds_read_b128 v[2:5], v14
	ds_read_b128 v[6:9], v14 offset:32
	s_waitcnt lgkmcnt(1)
	s_nop 0
	v_mfma_f32_32x32x16_bf16 v[64:79], v[2:5], v[100:103], v[234:249]
	ds_read_b128 v[2:5], v14 offset:6656
	ds_read_b128 v[10:13], v14 offset:6688
	s_waitcnt lgkmcnt(1)
	v_mfma_f32_32x32x16_bf16 v[48:63], v[2:5], v[100:103], v[234:249]
	v_mfma_f32_32x32x16_bf16 v[64:79], v[6:9], v[80:83], v[64:79]
	ds_read_b128 v[2:5], v14 offset:64
	ds_read_b128 v[6:9], v14 offset:96
	s_waitcnt lgkmcnt(2)
	v_mfma_f32_32x32x16_bf16 v[48:63], v[10:13], v[80:83], v[48:63]
	s_waitcnt lgkmcnt(1)
	v_mfma_f32_32x32x16_bf16 v[64:79], v[2:5], v[84:87], v[64:79]
	ds_read_b128 v[2:5], v14 offset:6720
	ds_read_b128 v[10:13], v14 offset:6752
	s_waitcnt lgkmcnt(1)
	v_mfma_f32_32x32x16_bf16 v[48:63], v[2:5], v[84:87], v[48:63]
	v_mfma_f32_32x32x16_bf16 v[64:79], v[6:9], v[88:91], v[64:79]
	ds_read_b128 v[2:5], v14 offset:128
	ds_read_b128 v[6:9], v14 offset:160
	s_waitcnt lgkmcnt(2)
	v_mfma_f32_32x32x16_bf16 v[48:63], v[10:13], v[88:91], v[48:63]
	s_waitcnt lgkmcnt(1)
	v_mfma_f32_32x32x16_bf16 v[64:79], v[2:5], v[92:95], v[64:79]
	ds_read_b128 v[2:5], v14 offset:6784
	ds_read_b128 v[10:13], v14 offset:6816
	s_waitcnt lgkmcnt(1)
	v_mfma_f32_32x32x16_bf16 v[48:63], v[2:5], v[92:95], v[48:63]
	s_waitcnt lgkmcnt(0)
	v_mfma_f32_32x32x16_bf16 v[48:63], v[10:13], v[96:99], v[48:63]
	v_mfma_f32_32x32x16_bf16 v[64:79], v[6:9], v[96:99], v[64:79]
	s_nop 10
	v_max_f32_e32 v2, v48, v48
	v_max_f32_e32 v3, v64, v64
	v_max_f32_e32 v2, v3, v2
	v_max3_f32 v2, v2, v65, v49
	v_max3_f32 v2, v2, v66, v50
	v_max3_f32 v2, v2, v67, v51
	v_max3_f32 v2, v2, v68, v52
	v_max3_f32 v2, v2, v69, v53
	v_max3_f32 v2, v2, v70, v54
	v_max3_f32 v2, v2, v71, v55
	v_max3_f32 v2, v2, v72, v56
	v_max3_f32 v2, v2, v73, v57
	v_max3_f32 v2, v2, v74, v58
	v_max3_f32 v2, v2, v75, v59
	v_max3_f32 v2, v2, v76, v60
	v_max3_f32 v2, v2, v77, v61
	v_max3_f32 v2, v2, v78, v62
	v_max3_f32 v2, v2, v79, v63
	ds_bpermute_b32 v3, v171, v2
	s_waitcnt lgkmcnt(0)
	v_max_f32_e32 v3, v3, v3
	v_max_f32_e32 v2, v2, v3
	v_cmp_lt_f32_e32 vcc, s26, v2
	s_cbranch_vccz .LBB0_572
	v_max_f32_e32 v2, v2, v2
	v_max_f32_e32 v2, 0, v2
	v_exp_f32_e64 v4, -v2
	v_pk_add_f32 v[64:65], v[64:65], v[2:3] op_sel_hi:[1,0] neg_lo:[0,1] neg_hi:[0,1]
	v_pk_add_f32 v[48:49], v[48:49], v[2:3] op_sel_hi:[1,0] neg_lo:[0,1] neg_hi:[0,1]
	v_pk_add_f32 v[66:67], v[66:67], v[2:3] op_sel_hi:[1,0] neg_lo:[0,1] neg_hi:[0,1]
	v_pk_add_f32 v[50:51], v[50:51], v[2:3] op_sel_hi:[1,0] neg_lo:[0,1] neg_hi:[0,1]
	v_pk_add_f32 v[68:69], v[68:69], v[2:3] op_sel_hi:[1,0] neg_lo:[0,1] neg_hi:[0,1]
	v_pk_add_f32 v[52:53], v[52:53], v[2:3] op_sel_hi:[1,0] neg_lo:[0,1] neg_hi:[0,1]
	v_pk_add_f32 v[70:71], v[70:71], v[2:3] op_sel_hi:[1,0] neg_lo:[0,1] neg_hi:[0,1]
	v_pk_add_f32 v[54:55], v[54:55], v[2:3] op_sel_hi:[1,0] neg_lo:[0,1] neg_hi:[0,1]
	v_pk_add_f32 v[72:73], v[72:73], v[2:3] op_sel_hi:[1,0] neg_lo:[0,1] neg_hi:[0,1]
	v_pk_add_f32 v[56:57], v[56:57], v[2:3] op_sel_hi:[1,0] neg_lo:[0,1] neg_hi:[0,1]
	v_pk_add_f32 v[74:75], v[74:75], v[2:3] op_sel_hi:[1,0] neg_lo:[0,1] neg_hi:[0,1]
	v_pk_add_f32 v[58:59], v[58:59], v[2:3] op_sel_hi:[1,0] neg_lo:[0,1] neg_hi:[0,1]
	v_pk_add_f32 v[76:77], v[76:77], v[2:3] op_sel_hi:[1,0] neg_lo:[0,1] neg_hi:[0,1]
	v_pk_add_f32 v[60:61], v[60:61], v[2:3] op_sel_hi:[1,0] neg_lo:[0,1] neg_hi:[0,1]
	v_pk_mul_f32 v[46:47], v[46:47], v[4:5] op_sel_hi:[1,0]
	v_pk_mul_f32 v[44:45], v[44:45], v[4:5] op_sel_hi:[1,0]
	v_pk_mul_f32 v[42:43], v[42:43], v[4:5] op_sel_hi:[1,0]
	v_pk_mul_f32 v[40:41], v[40:41], v[4:5] op_sel_hi:[1,0]
	v_pk_mul_f32 v[38:39], v[38:39], v[4:5] op_sel_hi:[1,0]
	v_pk_mul_f32 v[36:37], v[36:37], v[4:5] op_sel_hi:[1,0]
	v_pk_mul_f32 v[34:35], v[34:35], v[4:5] op_sel_hi:[1,0]
	v_pk_mul_f32 v[32:33], v[32:33], v[4:5] op_sel_hi:[1,0]
	v_pk_mul_f32 v[30:31], v[30:31], v[4:5] op_sel_hi:[1,0]
	v_pk_mul_f32 v[28:29], v[28:29], v[4:5] op_sel_hi:[1,0]
	v_pk_mul_f32 v[26:27], v[26:27], v[4:5] op_sel_hi:[1,0]
	v_pk_mul_f32 v[24:25], v[24:25], v[4:5] op_sel_hi:[1,0]
	v_pk_mul_f32 v[22:23], v[22:23], v[4:5] op_sel_hi:[1,0]
	v_pk_mul_f32 v[20:21], v[20:21], v[4:5] op_sel_hi:[1,0]
	v_pk_mul_f32 v[18:19], v[18:19], v[4:5] op_sel_hi:[1,0]
	v_pk_mul_f32 v[16:17], v[16:17], v[4:5] op_sel_hi:[1,0]
	v_pk_add_f32 v[78:79], v[78:79], v[2:3] op_sel_hi:[1,0] neg_lo:[0,1] neg_hi:[0,1]
	v_pk_add_f32 v[62:63], v[62:63], v[2:3] op_sel_hi:[1,0] neg_lo:[0,1] neg_hi:[0,1]
	v_mul_f32_e32 v173, v173, v4
	v_add_f32_e32 v0, v0, v2
	v_xor_b32_e32 v234, 0x80000000, v0
	v_mov_b32_e32 v235, v234
	v_mov_b32_e32 v236, v234
	v_mov_b32_e32 v237, v234
	v_mov_b32_e32 v238, v234
	v_mov_b32_e32 v239, v234
	v_mov_b32_e32 v240, v234
	v_mov_b32_e32 v241, v234
	v_mov_b32_e32 v242, v234
	v_mov_b32_e32 v243, v234
	v_mov_b32_e32 v244, v234
	v_mov_b32_e32 v245, v234
	v_mov_b32_e32 v246, v234
	v_mov_b32_e32 v247, v234
	v_mov_b32_e32 v248, v234
	v_mov_b32_e32 v249, v234

.LBB0_578:
	s_or_b64 exec, exec, s[6:7]
	s_waitcnt lgkmcnt(0)
	s_barrier
	ds_read_b128 v[222:225], v198 offset:22528
	ds_read_b128 v[226:229], v198 offset:22560
	v_add_f32_e32 v6, 0, v6
	v_add_f32_e32 v6, v6, v7
	s_waitcnt lgkmcnt(1)
	v_mfma_f32_32x32x16_bf16 v[64:79], v[222:225], v[100:103], v[234:249]
	ds_read_b128 v[222:225], v198 offset:29184
	ds_read_b128 v[230:233], v198 offset:29216
	v_add_f32_e32 v6, v8, v6
	v_add_f32_e32 v6, v9, v6
	v_add_f32_e32 v10, v10, v6
	v_add_f32_e32 v3, v3, v10
	v_add_f32_e32 v3, v4, v3
	v_add_f32_e32 v3, v5, v3
	s_waitcnt lgkmcnt(1)
	v_mfma_f32_32x32x16_bf16 v[48:63], v[222:225], v[100:103], v[234:249]
	v_add_f32_e32 v3, v15, v3
	v_add_f32_e32 v3, v175, v3
	v_add_f32_e32 v3, v11, v3
	v_add_f32_e32 v3, v177, v3
	v_add_f32_e32 v3, v179, v3
	v_add_f32_e32 v3, v205, v3
	v_add_f32_e32 v3, v206, v3
	v_mfma_f32_32x32x16_bf16 v[64:79], v[226:229], v[80:83], v[64:79]
	ds_read_b128 v[222:225], v198 offset:22592
	ds_read_b128 v[226:229], v198 offset:22624
	v_add_f32_e32 v3, v207, v3
	v_add_f32_e32 v3, v208, v3
	v_add_f32_e32 v3, v209, v3
	v_add_f32_e32 v3, v210, v3
	v_add_f32_e32 v3, v212, v3
	v_add_f32_e32 v3, v213, v3
	s_waitcnt lgkmcnt(2)
	v_mfma_f32_32x32x16_bf16 v[48:63], v[230:233], v[80:83], v[48:63]
	v_add_f32_e32 v3, v214, v3
	v_add_f32_e32 v3, v215, v3
	v_add_f32_e32 v3, v211, v3
	v_add_f32_e32 v3, v216, v3
	v_add_f32_e32 v3, v217, v3
	v_add_f32_e32 v3, v218, v3
	v_add_f32_e32 v3, v219, v3
	s_waitcnt lgkmcnt(1)
	v_mfma_f32_32x32x16_bf16 v[64:79], v[222:225], v[84:87], v[64:79]
	ds_read_b128 v[222:225], v198 offset:29248
	ds_read_b128 v[230:233], v198 offset:29280
	ds_read_b128 v[6:9], v198 offset:22656
	v_add_f32_e32 v3, v220, v3
	v_add_f32_e32 v3, v12, v3
	v_add_f32_e32 v3, v13, v3
	v_add_f32_e32 v3, v14, v3
	v_add_f32_e32 v3, v173, v3
	s_waitcnt lgkmcnt(2)
	v_mfma_f32_32x32x16_bf16 v[48:63], v[222:225], v[84:87], v[48:63]
	v_mfma_f32_32x32x16_bf16 v[64:79], v[226:229], v[88:91], v[64:79]
	ds_read_b128 v[222:225], v198 offset:29312
	ds_read_b128 v[226:229], v198 offset:22688
	s_waitcnt lgkmcnt(3)
	v_mfma_f32_32x32x16_bf16 v[48:63], v[230:233], v[88:91], v[48:63]
	s_waitcnt lgkmcnt(2)
	v_mfma_f32_32x32x16_bf16 v[64:79], v[6:9], v[92:95], v[64:79]
	ds_read_b128 v[4:7], v198 offset:29344
	s_waitcnt lgkmcnt(2)
	v_mfma_f32_32x32x16_bf16 v[48:63], v[222:225], v[92:95], v[48:63]
	s_waitcnt lgkmcnt(0)
	v_mfma_f32_32x32x16_bf16 v[48:63], v[4:7], v[96:99], v[48:63]
	v_mfma_f32_32x32x16_bf16 v[64:79], v[226:229], v[96:99], v[64:79]
	s_nop 10
	v_max_f32_e32 v4, v48, v48
	v_max_f32_e32 v5, v64, v64
	v_max_f32_e32 v4, v5, v4
	v_max3_f32 v4, v4, v65, v49
	v_max3_f32 v4, v4, v66, v50
	v_max3_f32 v4, v4, v67, v51
	v_max3_f32 v4, v4, v68, v52
	v_max3_f32 v4, v4, v69, v53
	v_max3_f32 v4, v4, v70, v54
	v_max3_f32 v4, v4, v71, v55
	v_max3_f32 v4, v4, v72, v56
	v_max3_f32 v4, v4, v73, v57
	v_max3_f32 v4, v4, v74, v58
	v_max3_f32 v4, v4, v75, v59
	v_max3_f32 v4, v4, v76, v60
	v_max3_f32 v4, v4, v77, v61
	v_max3_f32 v4, v4, v78, v62
	v_max3_f32 v4, v4, v79, v63
	ds_bpermute_b32 v5, v171, v4
	s_waitcnt lgkmcnt(0)
	v_max_f32_e32 v5, v5, v5
	v_max_f32_e32 v4, v4, v5
	v_cmp_lt_f32_e32 vcc, s26, v4
	s_cbranch_vccz .LBB0_580
	v_max_f32_e32 v4, v4, v4
	v_max_f32_e32 v4, 0, v4
	v_exp_f32_e64 v6, -v4
	v_pk_add_f32 v[64:65], v[64:65], v[4:5] op_sel_hi:[1,0] neg_lo:[0,1] neg_hi:[0,1]
	v_pk_add_f32 v[48:49], v[48:49], v[4:5] op_sel_hi:[1,0] neg_lo:[0,1] neg_hi:[0,1]
	v_pk_add_f32 v[66:67], v[66:67], v[4:5] op_sel_hi:[1,0] neg_lo:[0,1] neg_hi:[0,1]
	v_pk_add_f32 v[50:51], v[50:51], v[4:5] op_sel_hi:[1,0] neg_lo:[0,1] neg_hi:[0,1]
	v_pk_add_f32 v[68:69], v[68:69], v[4:5] op_sel_hi:[1,0] neg_lo:[0,1] neg_hi:[0,1]
	v_pk_add_f32 v[52:53], v[52:53], v[4:5] op_sel_hi:[1,0] neg_lo:[0,1] neg_hi:[0,1]
	v_pk_add_f32 v[70:71], v[70:71], v[4:5] op_sel_hi:[1,0] neg_lo:[0,1] neg_hi:[0,1]
	v_pk_add_f32 v[54:55], v[54:55], v[4:5] op_sel_hi:[1,0] neg_lo:[0,1] neg_hi:[0,1]
	v_pk_add_f32 v[72:73], v[72:73], v[4:5] op_sel_hi:[1,0] neg_lo:[0,1] neg_hi:[0,1]
	v_pk_add_f32 v[56:57], v[56:57], v[4:5] op_sel_hi:[1,0] neg_lo:[0,1] neg_hi:[0,1]
	v_pk_add_f32 v[74:75], v[74:75], v[4:5] op_sel_hi:[1,0] neg_lo:[0,1] neg_hi:[0,1]
	v_pk_add_f32 v[58:59], v[58:59], v[4:5] op_sel_hi:[1,0] neg_lo:[0,1] neg_hi:[0,1]
	v_pk_add_f32 v[76:77], v[76:77], v[4:5] op_sel_hi:[1,0] neg_lo:[0,1] neg_hi:[0,1]
	v_pk_add_f32 v[60:61], v[60:61], v[4:5] op_sel_hi:[1,0] neg_lo:[0,1] neg_hi:[0,1]
	v_pk_mul_f32 v[46:47], v[46:47], v[6:7] op_sel_hi:[1,0]
	v_pk_mul_f32 v[44:45], v[44:45], v[6:7] op_sel_hi:[1,0]
	v_pk_mul_f32 v[42:43], v[42:43], v[6:7] op_sel_hi:[1,0]
	v_pk_mul_f32 v[40:41], v[40:41], v[6:7] op_sel_hi:[1,0]
	v_pk_mul_f32 v[38:39], v[38:39], v[6:7] op_sel_hi:[1,0]
	v_pk_mul_f32 v[36:37], v[36:37], v[6:7] op_sel_hi:[1,0]
	v_pk_mul_f32 v[34:35], v[34:35], v[6:7] op_sel_hi:[1,0]
	v_pk_mul_f32 v[32:33], v[32:33], v[6:7] op_sel_hi:[1,0]
	v_pk_mul_f32 v[30:31], v[30:31], v[6:7] op_sel_hi:[1,0]
	v_pk_mul_f32 v[28:29], v[28:29], v[6:7] op_sel_hi:[1,0]
	v_pk_mul_f32 v[26:27], v[26:27], v[6:7] op_sel_hi:[1,0]
	v_pk_mul_f32 v[24:25], v[24:25], v[6:7] op_sel_hi:[1,0]
	v_pk_mul_f32 v[22:23], v[22:23], v[6:7] op_sel_hi:[1,0]
	v_pk_mul_f32 v[20:21], v[20:21], v[6:7] op_sel_hi:[1,0]
	v_pk_mul_f32 v[18:19], v[18:19], v[6:7] op_sel_hi:[1,0]
	v_pk_mul_f32 v[16:17], v[16:17], v[6:7] op_sel_hi:[1,0]
	v_pk_add_f32 v[78:79], v[78:79], v[4:5] op_sel_hi:[1,0] neg_lo:[0,1] neg_hi:[0,1]
	v_pk_add_f32 v[62:63], v[62:63], v[4:5] op_sel_hi:[1,0] neg_lo:[0,1] neg_hi:[0,1]
	v_mul_f32_e32 v3, v3, v6
	v_add_f32_e32 v0, v0, v4
	v_xor_b32_e32 v234, 0x80000000, v0
	v_mov_b32_e32 v235, v234
	v_mov_b32_e32 v236, v234
	v_mov_b32_e32 v237, v234
	v_mov_b32_e32 v238, v234
	v_mov_b32_e32 v239, v234
	v_mov_b32_e32 v240, v234
	v_mov_b32_e32 v241, v234
	v_mov_b32_e32 v242, v234
	v_mov_b32_e32 v243, v234
	v_mov_b32_e32 v244, v234
	v_mov_b32_e32 v245, v234
	v_mov_b32_e32 v246, v234
	v_mov_b32_e32 v247, v234
	v_mov_b32_e32 v248, v234
	v_mov_b32_e32 v249, v234
